# v9 + GEMM phase prologues: K-tile 1 stage loads issued before the first wait (vmcnt 8), overlapping both tiles' first-touch latency
# baseline (speedup 1.0000x reference)
; #define PG8_STAGE(bufoff, gbase, voff) do { _Pragma("unroll") for (int _i = 0; _i < 2; ++_i) \
;         __builtin_amdgcn_global_load_lds((const unsigned*)((const char*)(gbase) + (voff)[_i]), (PG8_LAS unsigned*)(lds + (bufoff) + ldsw + _i * 8192), 16, 0, 0); } while (0)
; #define PG8_WAIT_V(n) asm volatile("s_waitcnt vmcnt(" #n ")" ::: "memory")
; #define PG8_BAR __builtin_amdgcn_s_barrier()
; template <class Epi, class Sched, bool ALIGN_EPI = false, bool SP2 = false>
; __device__ __forceinline__ void gemm_phase(PG8_LAS unsigned char* lds, const Gemm g, const Sched& S, const Epi& E) {
;     ...
;     for (int i = 0; i < 2; ++i) { int R, C; stage_rc(tid * 16 + i * 8192, R, C); const int Rb = Epi::PERM ? ((R & ~31) + perm32(R & 31)) : R;
;         voffA[i] = (unsigned)(R * K + C) * 2u; voffB[i] = (unsigned)(Rb * K + C) * 2u; }
;     const size_t kstep = (size_t)(BK * 2);
;     const size_t hstep = (size_t)HALF * K * 2;
;     const size_t tstep = 2 * hstep;
;     const unsigned ldsw = (unsigned)wid * 1024u;
;     const int aoff = lds_byte(wr * 64 + fr, fq * 8), boff = lds_byte(wc * 32 + fr, fq * 8);
;     ...
;     if constexpr (SP2) {
;         PG8_STAGE(PG8_SB(0, 0), cB, voffB); PG8_STAGE(PG8_SB(0, 1), cB + hstep, voffB); PG8_STAGE(PG8_SA(0, 0), cA, voffA); PG8_STAGE(PG8_SA(0, 1), cA + hstep, voffA);
;         if (wr == 1) PG8_BAR;
;         PG8_WAIT_V(2); PG8_BAR;
;         PG8_STAGE(PG8_SB(1, 0), cB + kstep, voffB); PG8_STAGE(PG8_SA(1, 0), cA + kstep, voffA); PG8_STAGE(PG8_SB(1, 1), cB + hstep + kstep, voffB);
;         PG8_WAIT_V(6); PG8_BAR;
.LBB0_358:
	v_lshl_add_u64 v[10:11], s[18:19], 0, v[0:1]
	v_mov_b32_e32 v131, v1
	v_readlane_b32 s16, v254, 2
	s_lshl_b32 s6, s6, 5
	v_lshl_add_u64 v[12:13], s[18:19], 0, v[130:131]
	v_mov_b32_e32 v135, v1
	v_readlane_b32 s17, v254, 3
	s_and_b32 s9, s6, 0x60
	s_add_i32 m0, s25, 0x18000
	v_lshl_add_u64 v[10:11], v[10:11], 0, s[38:39]
	v_lshl_add_u64 v[14:15], s[16:17], 0, v[134:135]
	v_mov_b32_e32 v133, v1
	s_lshl_b32 s8, s5, 13
	s_lshl_b32 s10, s9, 7
	global_load_lds_dwordx4 v[10:11], off
	v_lshl_add_u64 v[10:11], v[12:13], 0, s[38:39]
	s_add_i32 m0, s25, 0x1a000
	s_add_i32 s29, s25, 0x8000
	s_add_i32 s30, s25, 0xa000
	v_lshl_add_u64 v[16:17], s[16:17], 0, v[132:133]
	global_load_lds_dwordx4 v[10:11], off
	v_lshl_add_u64 v[10:11], v[14:15], 0, s[38:39]
	s_mov_b32 m0, s29
	s_add_u32 s6, s18, 0x40080
	global_load_lds_dwordx4 v[10:11], off
	v_lshl_add_u64 v[10:11], v[16:17], 0, s[38:39]
	s_mov_b32 m0, s30
	s_addc_u32 s7, s19, 0
	global_load_lds_dwordx4 v[10:11], off
	s_add_i32 m0, s25, 0x1c000
	v_lshl_add_u64 v[10:11], s[6:7], 0, v[0:1]
	global_load_lds_dwordx4 v[10:11], off
	v_lshl_add_u64 v[10:11], s[6:7], 0, v[130:131]
	s_add_i32 m0, s25, 0x1e000
	v_and_b32_e32 v9, 15, v2
	global_load_lds_dwordx4 v[10:11], off
	s_waitcnt vmcnt(8)
	s_barrier
	v_lshrrev_b32_e32 v10, 1, v2
	v_and_b32_e32 v10, 24, v10
	v_lshlrev_b32_e32 v11, 1, v10
	v_lshlrev_b32_e32 v2, 2, v2
	v_lshl_or_b32 v142, s5, 6, v9
	v_lshl_or_b32 v9, v9, 6, v11
	v_and_b32_e32 v2, 32, v2
	v_bitop3_b32 v11, v9, s8, v2 bitop3:0xde
	v_bitop3_b32 v143, v9, s10, v2 bitop3:0xde
	v_lshlrev_b32_e32 v2, 14, v7
	v_and_b32_e32 v2, 0xffff8000, v2
	v_lshl_add_u32 v2, v6, 11, v2
	v_and_b32_e32 v6, 1, v7
	v_lshl_or_b32 v2, v6, 6, v2
	v_lshl_add_u32 v136, v8, 1, v2
	v_lshlrev_b32_e32 v2, 14, v3
	v_and_b32_e32 v2, 0xffff8000, v2
	s_waitcnt vmcnt(6)
	v_lshl_add_u32 v2, v4, 11, v2
	v_and_b32_e32 v3, 1, v3
	s_cmpk_lt_u32 s4, 0x100
	v_lshl_or_b32 v2, v3, 6, v2
	v_readlane_b32 s4, v254, 0
	s_cselect_b64 s[6:7], -1, 0
	v_or_b32_e32 v144, s9, v10
	v_mov_b32_e32 v137, v1
	v_lshl_add_u32 v138, v5, 1, v2
	v_mov_b32_e32 v139, v1
	s_mov_b32 s31, 0
	v_add_u32_e32 v145, 0, v11
	v_readlane_b32 s33, v253, 61
	s_mov_b32 s49, s4
	s_barrier
	v_readlane_b32 s5, v254, 1
	s_waitcnt vmcnt(0)
	s_branch .LBB0_361

; #define PG8_STAGE(bufoff, gbase, voff) do { _Pragma("unroll") for (int _i = 0; _i < 2; ++_i) \
;         __builtin_amdgcn_global_load_lds((const unsigned*)((const char*)(gbase) + (voff)[_i]), (PG8_LAS unsigned*)(lds + (bufoff) + ldsw + _i * 8192), 16, 0, 0); } while (0)
; #define PG8_WAIT_V(n) asm volatile("s_waitcnt vmcnt(" #n ")" ::: "memory")
; #define PG8_BAR __builtin_amdgcn_s_barrier()
; template <class Epi, class Sched, bool ALIGN_EPI = false, bool SP2 = false>
; __device__ __forceinline__ void gemm_phase(PG8_LAS unsigned char* lds, const Gemm g, const Sched& S, const Epi& E) {
;     ...
;     for (int i = 0; i < 2; ++i) { int R, C; stage_rc(tid * 16 + i * 8192, R, C); const int Rb = Epi::PERM ? ((R & ~31) + perm32(R & 31)) : R;
;         voffA[i] = (unsigned)(R * K + C) * 2u; voffB[i] = (unsigned)(Rb * K + C) * 2u; }
;     const size_t kstep = (size_t)(BK * 2);
;     const size_t hstep = (size_t)HALF * K * 2;
;     const size_t tstep = 2 * hstep;
;     const unsigned ldsw = (unsigned)wid * 1024u;
;     const int aoff = lds_byte(wr * 64 + fr, fq * 8), boff = lds_byte(wc * 32 + fr, fq * 8);
;     ...
;     if constexpr (SP2) {
;         PG8_STAGE(PG8_SB(0, 0), cB, voffB); PG8_STAGE(PG8_SB(0, 1), cB + hstep, voffB); PG8_STAGE(PG8_SA(0, 0), cA, voffA); PG8_STAGE(PG8_SA(0, 1), cA + hstep, voffA);
;         if (wr == 1) PG8_BAR;
;         PG8_WAIT_V(2); PG8_BAR;
;         PG8_STAGE(PG8_SB(1, 0), cB + kstep, voffB); PG8_STAGE(PG8_SA(1, 0), cA + kstep, voffA); PG8_STAGE(PG8_SB(1, 1), cB + hstep + kstep, voffB);
;         PG8_WAIT_V(6); PG8_BAR;
.LBB0_422:
	s_mul_i32 s86, s54, 0xc00
	s_lshl_b64 s[8:9], s[86:87], 2
	s_add_u32 s7, s7, s8
	s_addc_u32 s8, s10, s9
	v_lshrrev_b32_e32 v18, 1, v12
	s_add_u32 s29, s7, 0x2000
	v_and_b32_e32 v18, 24, v18
	v_readlane_b32 s16, v254, 19
	s_addc_u32 s30, s8, 0
	v_and_b32_e32 v13, 15, v12
	v_lshlrev_b32_e32 v19, 1, v18
	v_lshlrev_b32_e32 v12, 2, v12
	s_lshl_b32 s5, s5, 5
	v_mov_b32_e32 v159, v1
	v_readlane_b32 s17, v254, 20
	v_lshl_or_b32 v200, s6, 6, v13
	v_lshl_or_b32 v13, v13, 6, v19
	s_lshl_b32 s6, s6, 13
	v_and_b32_e32 v12, 32, v12
	s_and_b32 s5, s5, 0x60
	s_add_i32 m0, s25, 0x18000
	v_lshl_add_u64 v[2:3], v[2:3], 0, s[38:39]
	v_lshl_add_u64 v[14:15], s[16:17], 0, v[158:159]
	v_mov_b32_e32 v157, v1
	v_bitop3_b32 v19, v13, s6, v12 bitop3:0xde
	s_lshl_b32 s6, s5, 7
	global_load_lds_dwordx4 v[2:3], off
	v_lshl_add_u64 v[2:3], v[4:5], 0, s[38:39]
	s_add_i32 m0, s25, 0x1a000
	s_add_i32 s31, s25, 0x8000
	s_add_i32 s33, s25, 0xa000
	v_lshl_add_u64 v[16:17], s[16:17], 0, v[156:157]
	v_bitop3_b32 v201, v13, s6, v12 bitop3:0xde
	global_load_lds_dwordx4 v[2:3], off
	v_lshl_add_u64 v[2:3], v[14:15], 0, s[38:39]
	s_mov_b32 m0, s31
	s_add_u32 s6, s18, 0x100080
	global_load_lds_dwordx4 v[2:3], off
	v_lshl_add_u64 v[2:3], v[16:17], 0, s[38:39]
	s_mov_b32 m0, s33
	s_addc_u32 s7, s19, 0
	global_load_lds_dwordx4 v[2:3], off
	s_add_i32 m0, s25, 0x1c000
	v_lshl_add_u64 v[2:3], s[6:7], 0, v[0:1]
	global_load_lds_dwordx4 v[2:3], off
	v_lshl_add_u64 v[2:3], s[6:7], 0, v[154:155]
	s_add_i32 m0, s25, 0x1e000
	s_cmpk_lt_u32 s4, 0x100
	global_load_lds_dwordx4 v[2:3], off
	s_waitcnt vmcnt(8)
	s_barrier
	v_lshlrev_b32_e32 v2, 16, v10
	v_and_b32_e32 v2, 0xfffe0000, v2
	v_lshl_add_u32 v2, v9, 13, v2
	v_and_b32_e32 v3, 1, v10
	v_lshl_or_b32 v2, v3, 6, v2
	v_lshl_add_u32 v160, v11, 1, v2
	v_lshlrev_b32_e32 v2, 16, v6
	v_and_b32_e32 v2, 0xfffe0000, v2
	s_waitcnt vmcnt(6)
	v_lshl_add_u32 v2, v7, 13, v2
	v_and_b32_e32 v3, 1, v6
	v_or_b32_e32 v202, s5, v18
	v_lshl_or_b32 v2, v3, 6, v2
	v_readlane_b32 s4, v254, 16
	s_cselect_b64 s[6:7], -1, 0
	v_mov_b32_e32 v161, v1
	v_lshl_add_u32 v162, v8, 1, v2
	v_mov_b32_e32 v163, v1
	s_mov_b32 s48, 0
	v_add_u32_e32 v203, 0, v19
	v_readlane_b32 s50, v254, 7
	s_mov_b32 s49, s4
	s_barrier
	v_readlane_b32 s5, v254, 17
	s_waitcnt vmcnt(0)
	s_branch .LBB0_425

; #define PG8_STAGE(bufoff, gbase, voff) do { _Pragma("unroll") for (int _i = 0; _i < 2; ++_i) \
;         __builtin_amdgcn_global_load_lds((const unsigned*)((const char*)(gbase) + (voff)[_i]), (PG8_LAS unsigned*)(lds + (bufoff) + ldsw + _i * 8192), 16, 0, 0); } while (0)
; #define PG8_WAIT_V(n) asm volatile("s_waitcnt vmcnt(" #n ")" ::: "memory")
; #define PG8_BAR __builtin_amdgcn_s_barrier()
; template <class Epi, class Sched, bool ALIGN_EPI = false, bool SP2 = false>
; __device__ __forceinline__ void gemm_phase(PG8_LAS unsigned char* lds, const Gemm g, const Sched& S, const Epi& E) {
;     ...
;     for (int i = 0; i < 2; ++i) { int R, C; stage_rc(tid * 16 + i * 8192, R, C); const int Rb = Epi::PERM ? ((R & ~31) + perm32(R & 31)) : R;
;         voffA[i] = (unsigned)(R * K + C) * 2u; voffB[i] = (unsigned)(Rb * K + C) * 2u; }
;     const size_t kstep = (size_t)(BK * 2);
;     const size_t hstep = (size_t)HALF * K * 2;
;     const size_t tstep = 2 * hstep;
;     const unsigned ldsw = (unsigned)wid * 1024u;
;     const int aoff = lds_byte(wr * 64 + fr, fq * 8), boff = lds_byte(wc * 32 + fr, fq * 8);
;     ...
;     if constexpr (SP2) {
;         PG8_STAGE(PG8_SB(0, 0), cB, voffB); PG8_STAGE(PG8_SB(0, 1), cB + hstep, voffB); PG8_STAGE(PG8_SA(0, 0), cA, voffA); PG8_STAGE(PG8_SA(0, 1), cA + hstep, voffA);
;         if (wr == 1) PG8_BAR;
;         PG8_WAIT_V(2); PG8_BAR;
;         PG8_STAGE(PG8_SB(1, 0), cB + kstep, voffB); PG8_STAGE(PG8_SA(1, 0), cA + kstep, voffA); PG8_STAGE(PG8_SB(1, 1), cB + hstep + kstep, voffB);
;         PG8_WAIT_V(6); PG8_BAR;
.LBB0_552:
	s_and_b64 s[8:9], s[44:45], exec
	s_movk_i32 s8, 0xc00
	s_cselect_b32 s44, s8, 0x1000
	s_cselect_b32 s45, 12, 16
	s_cselect_b32 s54, 0, 8
	s_and_b32 s7, s7, 3
	s_add_i32 m0, s50, 0x18000
	v_lshl_add_u64 v[8:9], v[8:9], 0, s[38:39]
	s_lshl_b32 s10, s6, 13
	s_lshl_b32 s11, s7, 12
	global_load_lds_dwordx4 v[8:9], off
	v_lshl_add_u64 v[6:7], v[6:7], 0, s[38:39]
	s_add_i32 m0, s50, 0x1a000
	s_add_i32 s55, s50, 0x8000
	s_add_i32 s56, s50, 0xa000
	global_load_lds_dwordx4 v[6:7], off
	v_lshl_add_u64 v[2:3], v[2:3], 0, s[38:39]
	s_mov_b32 m0, s55
	s_add_u32 s8, s24, 0x40080
	global_load_lds_dwordx4 v[2:3], off
	v_lshl_add_u64 v[2:3], v[4:5], 0, s[38:39]
	s_mov_b32 m0, s56
	s_addc_u32 s9, s25, 0
	global_load_lds_dwordx4 v[2:3], off
	s_add_i32 m0, s50, 0x1c000
	v_lshl_add_u64 v[2:3], s[8:9], 0, v[158:159]
	global_load_lds_dwordx4 v[2:3], off
	v_lshl_add_u64 v[2:3], s[8:9], 0, v[154:155]
	s_add_i32 m0, s50, 0x1e000
	v_bfe_u32 v4, v0, 4, 2
	global_load_lds_dwordx4 v[2:3], off
	s_waitcnt vmcnt(8)
	s_barrier
	v_and_b32_e32 v3, 15, v0
	v_lshlrev_b32_e32 v5, 4, v4
	v_lshlrev_b32_e32 v0, 2, v0
	v_lshl_or_b32 v174, s6, 6, v3
	v_lshl_or_b32 v3, v3, 6, v5
	v_and_b32_e32 v0, 32, v0
	v_bitop3_b32 v5, v3, s10, v0 bitop3:0xde
	v_bitop3_b32 v175, v3, s11, v0 bitop3:0xde
	v_lshlrev_b32_e32 v3, 14, v14
	v_and_b32_e32 v3, 0xffff8000, v3
	s_sext_i32_i16 s59, s4
	v_lshlrev_b32_e32 v2, 3, v4
	s_cmpk_lt_u32 s5, 0x100
	v_cmp_lt_u32_e64 s[4:5], 1, v4
	v_lshlrev_b32_e32 v0, 5, v4
	v_lshl_add_u32 v3, v13, 11, v3
	v_and_b32_e32 v4, 1, v14
	v_lshl_or_b32 v3, v4, 6, v3
	v_lshl_add_u32 v164, v15, 1, v3
	v_lshlrev_b32_e32 v3, 14, v10
	v_readlane_b32 s12, v253, 40
	v_and_b32_e32 v3, 0xffff8000, v3
	s_waitcnt vmcnt(6)
	v_readlane_b32 s13, v253, 41
	v_lshl_add_u32 v3, v11, 11, v3
	v_and_b32_e32 v4, 1, v10
	s_cselect_b64 s[8:9], -1, 0
	s_cmp_lg_u32 s7, 0
	v_lshl_add_u64 v[162:163], s[12:13], 0, v[0:1]
	v_lshl_or_b32 v0, s7, 5, v2
	v_lshl_or_b32 v3, v4, 6, v3
	s_mov_b32 s57, 0
	s_cselect_b64 s[10:11], -1, 0
	s_lshr_b32 s58, s54, 1
	v_lshl_or_b32 v176, s7, 6, v2
	v_mov_b32_e32 v165, v1
	v_lshl_add_u32 v166, v12, 1, v3
	v_mov_b32_e32 v167, v1
	v_add_u32_e32 v177, 0, v5
	v_lshlrev_b32_e32 v178, 1, v0
	v_lshlrev_b32_e32 v179, 2, v2
	s_barrier
	s_branch .LBB0_555

; #define PG8_STAGE(bufoff, gbase, voff) do { _Pragma("unroll") for (int _i = 0; _i < 2; ++_i) \
;         __builtin_amdgcn_global_load_lds((const unsigned*)((const char*)(gbase) + (voff)[_i]), (PG8_LAS unsigned*)(lds + (bufoff) + ldsw + _i * 8192), 16, 0, 0); } while (0)
; #define PG8_WAIT_V(n) asm volatile("s_waitcnt vmcnt(" #n ")" ::: "memory")
; #define PG8_BAR __builtin_amdgcn_s_barrier()
; template <class Epi, class Sched, bool ALIGN_EPI = false, bool SP2 = false>
; __device__ __forceinline__ void gemm_phase(PG8_LAS unsigned char* lds, const Gemm g, const Sched& S, const Epi& E) {
;     ...
;     for (int i = 0; i < 2; ++i) { int R, C; stage_rc(tid * 16 + i * 8192, R, C); const int Rb = Epi::PERM ? ((R & ~31) + perm32(R & 31)) : R;
;         voffA[i] = (unsigned)(R * K + C) * 2u; voffB[i] = (unsigned)(Rb * K + C) * 2u; }
;     const size_t kstep = (size_t)(BK * 2);
;     const size_t hstep = (size_t)HALF * K * 2;
;     const size_t tstep = 2 * hstep;
;     const unsigned ldsw = (unsigned)wid * 1024u;
;     const int aoff = lds_byte(wr * 64 + fr, fq * 8), boff = lds_byte(wc * 32 + fr, fq * 8);
;     ...
;     if constexpr (SP2) {
;         PG8_STAGE(PG8_SB(0, 0), cB, voffB); PG8_STAGE(PG8_SB(0, 1), cB + hstep, voffB); PG8_STAGE(PG8_SA(0, 0), cA, voffA); PG8_STAGE(PG8_SA(0, 1), cA + hstep, voffA);
;         if (wr == 1) PG8_BAR;
;         PG8_WAIT_V(2); PG8_BAR;
;         PG8_STAGE(PG8_SB(1, 0), cB + kstep, voffB); PG8_STAGE(PG8_SA(1, 0), cA + kstep, voffA); PG8_STAGE(PG8_SB(1, 1), cB + hstep + kstep, voffB);
;         PG8_WAIT_V(6); PG8_BAR;
.LBB0_1080:
	v_readlane_b32 s7, v255, 2
	s_waitcnt vmcnt(0)
	v_lshrrev_b32_e32 v18, 1, v12
	s_add_u32 s29, s7, 0x5000
	v_readlane_b32 s7, v255, 3
	v_and_b32_e32 v18, 24, v18
	v_readlane_b32 s16, v254, 10
	s_addc_u32 s30, s7, 0
	v_and_b32_e32 v13, 15, v12
	v_lshlrev_b32_e32 v19, 1, v18
	v_lshlrev_b32_e32 v12, 2, v12
	s_lshl_b32 s5, s5, 5
	v_mov_b32_e32 v135, v1
	v_readlane_b32 s17, v254, 11
	v_lshl_or_b32 v166, s6, 6, v13
	v_lshl_or_b32 v13, v13, 6, v19
	s_lshl_b32 s6, s6, 13
	v_and_b32_e32 v12, 32, v12
	s_and_b32 s5, s5, 0x60
	s_add_i32 m0, s25, 0x18000
	v_lshl_add_u64 v[2:3], v[2:3], 0, s[38:39]
	v_lshl_add_u64 v[14:15], s[16:17], 0, v[134:135]
	v_mov_b32_e32 v133, v1
	v_bitop3_b32 v19, v13, s6, v12 bitop3:0xde
	s_lshl_b32 s6, s5, 7
	global_load_lds_dwordx4 v[2:3], off
	v_lshl_add_u64 v[2:3], v[4:5], 0, s[38:39]
	s_add_i32 m0, s25, 0x1a000
	s_add_i32 s31, s25, 0x8000
	s_add_i32 s33, s25, 0xa000
	v_lshl_add_u64 v[16:17], s[16:17], 0, v[132:133]
	v_bitop3_b32 v167, v13, s6, v12 bitop3:0xde
	global_load_lds_dwordx4 v[2:3], off
	v_lshl_add_u64 v[2:3], v[14:15], 0, s[38:39]
	s_mov_b32 m0, s31
	s_add_u32 s6, s18, 0x40080
	global_load_lds_dwordx4 v[2:3], off
	v_lshl_add_u64 v[2:3], v[16:17], 0, s[38:39]
	s_mov_b32 m0, s33
	s_addc_u32 s7, s19, 0
	global_load_lds_dwordx4 v[2:3], off
	s_add_i32 m0, s25, 0x1c000
	v_lshl_add_u64 v[2:3], s[6:7], 0, v[0:1]
	global_load_lds_dwordx4 v[2:3], off
	v_lshl_add_u64 v[2:3], s[6:7], 0, v[130:131]
	s_add_i32 m0, s25, 0x1e000
	s_cmpk_lt_u32 s4, 0x100
	global_load_lds_dwordx4 v[2:3], off
	s_waitcnt vmcnt(8)
	s_barrier
	v_lshlrev_b32_e32 v2, 14, v10
	v_and_b32_e32 v2, 0xffff8000, v2
	v_lshl_add_u32 v2, v9, 11, v2
	v_and_b32_e32 v3, 1, v10
	v_lshl_or_b32 v2, v3, 6, v2
	v_lshl_add_u32 v136, v11, 1, v2
	v_lshlrev_b32_e32 v2, 14, v6
	v_and_b32_e32 v2, 0xffff8000, v2
	s_waitcnt vmcnt(6)
	v_lshl_add_u32 v2, v7, 11, v2
	v_and_b32_e32 v3, 1, v6
	v_or_b32_e32 v168, s5, v18
	v_lshl_or_b32 v2, v3, 6, v2
	v_readlane_b32 s4, v254, 16
	s_cselect_b64 s[6:7], -1, 0
	v_mov_b32_e32 v137, v1
	v_lshl_add_u32 v138, v8, 1, v2
	v_mov_b32_e32 v139, v1
	s_mov_b32 s34, 0
	v_add_u32_e32 v169, 0, v19
	v_readlane_b32 s44, v254, 7
	s_mov_b32 s35, s4
	s_barrier
	v_readlane_b32 s5, v254, 17
	s_waitcnt vmcnt(0)
	s_branch .LBB0_1083
